# GEMM tile headers: generic u32 division (v_rcp + readfirstlane + SALU fixup) by the constant group height 8 replaced with shift and mask
# baseline (speedup 1.0000x reference)
.LBB0_54:
	s_add_i32 s88, s88, 1
	s_mul_i32 s6, s88, s79
	s_mul_hi_u32 s7, s88, s78
	s_add_i32 s7, s7, s6
	s_mul_i32 s6, s88, s78
	s_add_u32 s6, s6, s82
	s_addc_u32 s7, s7, s81
	v_cmp_gt_i64_e32 vcc, s[6:7], v[192:193]
	s_mov_b32 s70, s82
	v_cmp_lt_i64_e64 s[42:43], s[6:7], v[190:191]
	s_cbranch_vccnz .LBB0_56
	s_ashr_i32 s7, s6, 31
	s_lshr_b32 s7, s7, 29
	s_add_i32 s7, s6, s7
	s_ashr_i32 s9, s7, 3
	s_and_b32 s7, s7, -8
	s_sub_i32 s6, s6, s7
	s_cmp_lt_i32 s6, 0
	s_movk_i32 s7, 0x181
	s_cselect_b32 s7, s7, 0x180
	s_mul_i32 s6, s6, s7
	s_add_i32 s6, s6, s9
	s_mul_hi_i32 s7, s6, 0x2aaaaaab
	s_lshr_b32 s9, s7, 31
	s_ashr_i32 s7, s7, 4
	s_add_i32 s7, s7, s9
	s_lshl_b32 s9, s7, 3
	s_mulk_i32 s7, 0x60
	s_sub_i32 s6, s6, s7
	s_lshr_b32 s92, s6, 3
	s_and_b32 s6, s6, 7
	s_add_i32 s94, s9, s6
	s_lshr_b32 s6, s9, 3
	s_and_b32 s6, s6, 3
	s_add_i32 s92, s92, s6
	s_add_i32 s6, s92, -12
	s_cmp_gt_i32 s92, 11
	s_cselect_b32 s92, s6, s92

.LBB0_1368:
	s_ashr_i32 s6, s8, 3
	s_add_i32 s6, s10, s6
	s_ashr_i32 s7, s6, 31
	s_lshr_b32 s7, s7, 27
	s_add_i32 s7, s6, s7
	s_ashr_i32 s8, s7, 5
	s_lshl_b32 s8, s8, 3
	s_andn2_b32 s7, s7, 31
	s_sub_i32 s7, s6, s7
	s_lshr_b32 s6, s7, 3
	s_and_b32 s7, s7, 7
	s_add_i32 s8, s8, s7
